# RWKV per-tile k/a/decay stage: four rows interleaved (LDS reads hoisted, wave reductions 4-way interleaved, dead denorm-rescale removed)
# speedup vs baseline: 1.0035x; 1.0001x over previous
.LBB0_624:
	s_or_b64 exec, exec, s[0:1]
	s_waitcnt lgkmcnt(0)
	s_barrier
	s_and_saveexec_b64 s[0:1], s[4:5]
	s_xor_b64 s[0:1], exec, s[0:1]
	s_cbranch_execz .LBB0_635
	s_cmp_eq_u32 s18, 0xee2000
	s_cbranch_scc1 .LBB0_635
	s_andn2_b32 s20, 1, s25
	s_mul_i32 s21, s20, 0x6000
	s_add_i32 s23, s21, 0
	s_lshl_b32 s22, s20, 4
	v_lshl_add_u32 v200, v85, 2, s23
	v_lshl_add_u32 v201, v86, 2, s23
	v_lshl_add_u32 v202, v87, 2, s23
	v_lshl_add_u32 v203, v88, 2, s23
	ds_read2st64_b32 v[204:205], v200 offset0:16 offset1:32
	ds_read2st64_b32 v[206:207], v201 offset0:16 offset1:32
	ds_read2st64_b32 v[208:209], v202 offset0:16 offset1:32
	ds_read2st64_b32 v[210:211], v203 offset0:16 offset1:32
	ds_read2st64_b32 v[212:213], v200 offset0:48 offset1:64
	ds_read2st64_b32 v[214:215], v201 offset0:48 offset1:64
	ds_read2st64_b32 v[216:217], v202 offset0:48 offset1:64
	ds_read2st64_b32 v[218:219], v203 offset0:48 offset1:64
	s_waitcnt lgkmcnt(4)
	v_add_f32_e32 v220, v82, v204
	v_add_f32_e32 v221, v82, v206
	v_add_f32_e32 v222, v82, v208
	v_add_f32_e32 v223, v82, v210
	v_mul_f32_e32 v220, 0xbfb8aa3b, v220
	v_mul_f32_e32 v221, 0xbfb8aa3b, v221
	v_mul_f32_e32 v222, 0xbfb8aa3b, v222
	v_mul_f32_e32 v223, 0xbfb8aa3b, v223
	v_exp_f32_e32 v220, v220
	v_exp_f32_e32 v221, v221
	v_exp_f32_e32 v222, v222
	v_exp_f32_e32 v223, v223
	v_add_f32_e32 v224, v81, v205
	v_add_f32_e32 v225, v81, v207
	v_add_f32_e32 v226, v81, v209
	v_add_f32_e32 v227, v81, v211
	v_add_f32_e32 v220, 1.0, v220
	v_add_f32_e32 v221, 1.0, v221
	v_add_f32_e32 v222, 1.0, v222
	v_add_f32_e32 v223, 1.0, v223
	v_rcp_f32_e32 v220, v220
	v_rcp_f32_e32 v221, v221
	v_rcp_f32_e32 v222, v222
	v_rcp_f32_e32 v223, v223
	v_mul_f32_e32 v224, 0xbfb8aa3b, v224
	v_mul_f32_e32 v225, 0xbfb8aa3b, v225
	v_mul_f32_e32 v226, 0xbfb8aa3b, v226
	v_mul_f32_e32 v227, 0xbfb8aa3b, v227
	v_mul_f32_e32 v220, 0xbf1b4598, v220
	v_mul_f32_e32 v221, 0xbf1b4598, v221
	v_mul_f32_e32 v222, 0xbf1b4598, v222
	v_mul_f32_e32 v223, 0xbf1b4598, v223
	v_exp_f32_e32 v224, v224
	v_exp_f32_e32 v225, v225
	v_exp_f32_e32 v226, v226
	v_exp_f32_e32 v227, v227
	v_mul_f32_e32 v220, 0x3fb8aa3b, v220
	v_mul_f32_e32 v221, 0x3fb8aa3b, v221
	v_mul_f32_e32 v222, 0x3fb8aa3b, v222
	v_mul_f32_e32 v223, 0x3fb8aa3b, v223
	v_add_f32_e32 v224, 1.0, v224
	v_add_f32_e32 v225, 1.0, v225
	v_add_f32_e32 v226, 1.0, v226
	v_add_f32_e32 v227, 1.0, v227
	v_exp_f32_e32 v220, v220
	v_exp_f32_e32 v221, v221
	v_exp_f32_e32 v222, v222
	v_exp_f32_e32 v223, v223
	v_rcp_f32_e32 v224, v224
	v_rcp_f32_e32 v225, v225
	v_rcp_f32_e32 v226, v226
	v_rcp_f32_e32 v227, v227
	s_waitcnt lgkmcnt(0)
	v_mul_f32_e32 v228, v80, v212
	v_mul_f32_e32 v229, v80, v214
	v_mul_f32_e32 v230, v80, v216
	v_mul_f32_e32 v231, v80, v218
	v_mul_f32_e32 v232, v228, v228
	v_mul_f32_e32 v233, v229, v229
	v_mul_f32_e32 v234, v230, v230
	v_mul_f32_e32 v235, v231, v231
	v_mov_b32_dpp v232, v232 quad_perm:[1,0,3,2] row_mask:0xf bank_mask:0xf bound_ctrl:1
	v_mov_b32_dpp v233, v233 quad_perm:[1,0,3,2] row_mask:0xf bank_mask:0xf bound_ctrl:1
	v_mov_b32_dpp v234, v234 quad_perm:[1,0,3,2] row_mask:0xf bank_mask:0xf bound_ctrl:1
	v_mov_b32_dpp v235, v235 quad_perm:[1,0,3,2] row_mask:0xf bank_mask:0xf bound_ctrl:1
	v_fmac_f32_e32 v232, v228, v228
	v_fmac_f32_e32 v233, v229, v229
	v_fmac_f32_e32 v234, v230, v230
	v_fmac_f32_e32 v235, v231, v231
	v_add_f32_dpp v232, v232, v232 quad_perm:[2,3,0,1] row_mask:0xf bank_mask:0xf bound_ctrl:1
	v_add_f32_dpp v233, v233, v233 quad_perm:[2,3,0,1] row_mask:0xf bank_mask:0xf bound_ctrl:1
	v_add_f32_dpp v234, v234, v234 quad_perm:[2,3,0,1] row_mask:0xf bank_mask:0xf bound_ctrl:1
	v_add_f32_dpp v235, v235, v235 quad_perm:[2,3,0,1] row_mask:0xf bank_mask:0xf bound_ctrl:1
	v_add_f32_e32 v240, -1.0, v224
	v_add_f32_e32 v241, -1.0, v225
	v_add_f32_e32 v242, -1.0, v226
	v_add_f32_e32 v243, -1.0, v227
	v_add_f32_dpp v232, v232, v232 row_half_mirror row_mask:0xf bank_mask:0xf bound_ctrl:1
	v_add_f32_dpp v233, v233, v233 row_half_mirror row_mask:0xf bank_mask:0xf bound_ctrl:1
	v_add_f32_dpp v234, v234, v234 row_half_mirror row_mask:0xf bank_mask:0xf bound_ctrl:1
	v_add_f32_dpp v235, v235, v235 row_half_mirror row_mask:0xf bank_mask:0xf bound_ctrl:1
	v_fma_f32 v240, v79, v240, 1.0
	v_fma_f32 v241, v79, v241, 1.0
	v_fma_f32 v242, v79, v242, 1.0
	v_fma_f32 v243, v79, v243, 1.0
	v_add_f32_dpp v232, v232, v232 row_mirror row_mask:0xf bank_mask:0xf bound_ctrl:1
	v_add_f32_dpp v233, v233, v233 row_mirror row_mask:0xf bank_mask:0xf bound_ctrl:1
	v_add_f32_dpp v234, v234, v234 row_mirror row_mask:0xf bank_mask:0xf bound_ctrl:1
	v_add_f32_dpp v235, v235, v235 row_mirror row_mask:0xf bank_mask:0xf bound_ctrl:1
	v_mul_f32_e32 v244, v212, v240
	v_mul_f32_e32 v245, v214, v241
	v_mul_f32_e32 v246, v216, v242
	v_mul_f32_e32 v247, v218, v243
	v_add_f32_dpp v232, v232, v232 row_bcast:15 row_mask:0xa bank_mask:0xf
	v_add_f32_dpp v233, v233, v233 row_bcast:15 row_mask:0xa bank_mask:0xf
	v_add_f32_dpp v234, v234, v234 row_bcast:15 row_mask:0xa bank_mask:0xf
	v_add_f32_dpp v235, v235, v235 row_bcast:15 row_mask:0xa bank_mask:0xf
	v_mul_f32_e32 v213, v213, v244
	v_mul_f32_e32 v215, v215, v245
	v_mul_f32_e32 v217, v217, v246
	v_mul_f32_e32 v219, v219, v247
	v_add_f32_dpp v232, v232, v232 row_bcast:31 row_mask:0xc bank_mask:0xf
	v_add_f32_dpp v233, v233, v233 row_bcast:31 row_mask:0xc bank_mask:0xf
	v_add_f32_dpp v234, v234, v234 row_bcast:31 row_mask:0xc bank_mask:0xf
	v_add_f32_dpp v235, v235, v235 row_bcast:31 row_mask:0xc bank_mask:0xf
	v_mul_f32_e32 v236, v78, v213
	v_mul_f32_e32 v237, v78, v215
	v_mul_f32_e32 v238, v78, v217
	v_mul_f32_e32 v239, v78, v219
	v_readlane_b32 s20, v232, 63
	v_readlane_b32 s21, v233, 63
	v_readlane_b32 s26, v234, 63
	v_readlane_b32 s27, v235, 63
	v_mov_b32_dpp v236, v236 quad_perm:[1,0,3,2] row_mask:0xf bank_mask:0xf bound_ctrl:1
	v_mov_b32_dpp v237, v237 quad_perm:[1,0,3,2] row_mask:0xf bank_mask:0xf bound_ctrl:1
	v_mov_b32_dpp v238, v238 quad_perm:[1,0,3,2] row_mask:0xf bank_mask:0xf bound_ctrl:1
	v_mov_b32_dpp v239, v239 quad_perm:[1,0,3,2] row_mask:0xf bank_mask:0xf bound_ctrl:1
	v_add_f32_e32 v232, s20, v184
	v_add_f32_e32 v233, s21, v184
	v_add_f32_e32 v234, s26, v184
	v_add_f32_e32 v235, s27, v184
	v_fmac_f32_e32 v236, v78, v213
	v_fmac_f32_e32 v237, v78, v215
	v_fmac_f32_e32 v238, v78, v217
	v_fmac_f32_e32 v239, v78, v219
	v_rsq_f32_e32 v232, v232
	v_rsq_f32_e32 v233, v233
	v_rsq_f32_e32 v234, v234
	v_rsq_f32_e32 v235, v235
	v_add_f32_dpp v236, v236, v236 quad_perm:[2,3,0,1] row_mask:0xf bank_mask:0xf bound_ctrl:1
	v_add_f32_dpp v237, v237, v237 quad_perm:[2,3,0,1] row_mask:0xf bank_mask:0xf bound_ctrl:1
	v_add_f32_dpp v238, v238, v238 quad_perm:[2,3,0,1] row_mask:0xf bank_mask:0xf bound_ctrl:1
	v_add_f32_dpp v239, v239, v239 quad_perm:[2,3,0,1] row_mask:0xf bank_mask:0xf bound_ctrl:1
	v_mul_f32_e32 v228, v228, v232
	v_mul_f32_e32 v229, v229, v233
	v_mul_f32_e32 v230, v230, v234
	v_mul_f32_e32 v231, v231, v235
	v_add_f32_dpp v236, v236, v236 row_half_mirror row_mask:0xf bank_mask:0xf bound_ctrl:1
	v_add_f32_dpp v237, v237, v237 row_half_mirror row_mask:0xf bank_mask:0xf bound_ctrl:1
	v_add_f32_dpp v238, v238, v238 row_half_mirror row_mask:0xf bank_mask:0xf bound_ctrl:1
	v_add_f32_dpp v239, v239, v239 row_half_mirror row_mask:0xf bank_mask:0xf bound_ctrl:1
	ds_write2st64_b32 v200, v228, v220 offset1:16
	ds_write2st64_b32 v201, v229, v221 offset1:16
	ds_write2st64_b32 v202, v230, v222 offset1:16
	ds_write2st64_b32 v203, v231, v223 offset1:16
	v_add_f32_dpp v236, v236, v236 row_mirror row_mask:0xf bank_mask:0xf bound_ctrl:1
	v_add_f32_dpp v237, v237, v237 row_mirror row_mask:0xf bank_mask:0xf bound_ctrl:1
	v_add_f32_dpp v238, v238, v238 row_mirror row_mask:0xf bank_mask:0xf bound_ctrl:1
	v_add_f32_dpp v239, v239, v239 row_mirror row_mask:0xf bank_mask:0xf bound_ctrl:1
	v_mul_f32_e32 v240, v224, v228
	v_mul_f32_e32 v241, v225, v229
	v_mul_f32_e32 v242, v226, v230
	v_mul_f32_e32 v243, v227, v231
	v_add_f32_dpp v236, v236, v236 row_bcast:15 row_mask:0xa bank_mask:0xf
	v_add_f32_dpp v237, v237, v237 row_bcast:15 row_mask:0xa bank_mask:0xf
	v_add_f32_dpp v238, v238, v238 row_bcast:15 row_mask:0xa bank_mask:0xf
	v_add_f32_dpp v239, v239, v239 row_bcast:15 row_mask:0xa bank_mask:0xf
	ds_write2st64_b32 v200, v240, v244 offset0:32 offset1:48
	ds_write2st64_b32 v201, v241, v245 offset0:32 offset1:48
	ds_write2st64_b32 v202, v242, v246 offset0:32 offset1:48
	ds_write2st64_b32 v203, v243, v247 offset0:32 offset1:48
	v_add_f32_dpp v236, v236, v236 row_bcast:31 row_mask:0xc bank_mask:0xf
	v_add_f32_dpp v237, v237, v237 row_bcast:31 row_mask:0xc bank_mask:0xf
	v_add_f32_dpp v238, v238, v238 row_bcast:31 row_mask:0xc bank_mask:0xf
	v_add_f32_dpp v239, v239, v239 row_bcast:31 row_mask:0xc bank_mask:0xf
	s_nop 0
	v_readlane_b32 s20, v236, 63
	v_readlane_b32 s21, v237, 63
	v_readlane_b32 s26, v238, 63
	v_readlane_b32 s27, v239, 63
	s_nop 0
	v_mov_b32_e32 v1, s20
	v_mov_b32_e32 v2, s21
	v_mov_b32_e32 v3, s26
	v_mov_b32_e32 v36, s27
	s_and_saveexec_b64 s[30:31], s[16:17]
	v_lshl_add_u32 v37, s22, 2, v106
	ds_write_b32 v37, v1
	v_lshl_add_u32 v38, s22, 2, v144
	ds_write_b32 v38, v2
	v_lshl_add_u32 v39, s22, 2, v145
	ds_write_b32 v39, v3
	v_lshl_add_u32 v40, s22, 2, v146
	ds_write_b32 v40, v36
	s_or_b64 exec, exec, s[30:31]
